# v14: as v15 but the plain-GEMM epilogue's LDS read-back is not pipelined (only the up-GEMM one is)
# speedup vs baseline: 1.0971x; 1.0218x over previous
; __device__ __forceinline__ unsigned cvt_pk_bf16(float lo, float hi) { unsigned r; asm volatile("v_cvt_pk_bf16_f32 %0, %1, %2" : "=v"(r) : "v"(lo), "v"(hi)); return r; }
; __device__ __forceinline__ float relu_sq(float x) { float r; asm volatile("v_max_f32 %0, 0, %1" : "=v"(r) : "v"(x)); return r * r; }
;     __device__ __forceinline__ void operator()(const f32x4 (&acc)[2][2][4][2], const Unit& u, int wr, int wc, int fr, int fq) const {
;         const int row0 = u.pm * BM + wr * 64 + fr; const int col0 = u.pn * BM + wc * 32 + 8 * fq;
; #pragma unroll
;         for (int ai = 0; ai < 2; ++ai)
; #pragma unroll
;             for (int m = 0; m < 4; ++m) { const int row_ = row0 + ai * HALF + m * 16; bf16_t* rowp = O + (size_t)(row_ >> 11) * gs + (size_t)(row_ & 2047) * ldc + col0; const float sc = rs ? rs[row0 + ai * HALF + m * 16] : 1.f;
; #pragma unroll
;                 for (int bj = 0; bj < 2; ++bj) { f32x4 v0 = acc[ai][bj][m][0] * sc, v1 = acc[ai][bj][m][1] * sc;
;                     if (ACT == 1) {
; #pragma unroll
;                         for (int e = 0; e < 4; ++e) { v0[e] = relu_sq(v0[e]); v1[e] = relu_sq(v1[e]); } }
;                     u32x4 w; w.x = cvt_pk_bf16(v0[0], v0[1]); w.y = cvt_pk_bf16(v0[2], v0[3]); w.z = cvt_pk_bf16(v1[0], v1[1]); w.w = cvt_pk_bf16(v1[2], v1[3]);
;                     *(u32x4*)(rowp + bj * HALF) = w; } }
.Lupepi_go:
	global_load_dword v255, v129, s[100:101] sc1
	v_bfe_u32 v152, v186, 2, 4
	v_or_b32_e32 v150, s13, v152
	v_and_b32_e32 v187, 63, v186
	v_lshlrev_b32_e32 v187, 4, v187
	v_lshrrev_b32_e32 v152, 6, v186
	v_lshl_add_u32 v187, v152, 10, v187
	v_add_u32_e32 v187, 0x20000, v187
	v_and_b32_e32 v154, 15, v186
	v_bfe_u32 v148, v154, 1, 2
	v_bfe_u32 v149, v186, 4, 2
	v_xor_b32_e32 v148, v148, v149
	v_lshlrev_b32_e32 v148, 4, v148
	v_lshl_or_b32 v154, v154, 6, v148
	v_lshl_add_u32 v154, v152, 10, v154
	v_add_u32_e32 v154, 0x20000, v154
	v_bfe_u32 v152, v186, 3, 2
	v_and_b32_e32 v148, 3, v186
	v_xor_b32_e32 v152, v152, v148
	v_lshlrev_b32_e32 v152, 3, v152
	v_and_b32_e32 v148, 0xffffffe7, v156
	v_or_b32_e32 v152, v152, v148
.LBB0_40:
	s_ashr_i32 s13, s13, 11
	s_mul_hi_i32 s19, s13, 0x1040000
	s_mul_i32 s13, s13, 0x1040000
	v_and_b32_e32 v128, 0x7cf, v150
	s_add_u32 s18, s64, s13
	v_mul_u32_u24_e32 v128, 0x1040, v128
	s_waitcnt vmcnt(0)
	v_pk_mul_f32 v[124:125], v[124:125], v[200:201] op_sel_hi:[1,0]
	v_pk_mul_f32 v[120:121], v[120:121], v[200:201] op_sel_hi:[1,0]
	s_addc_u32 s19, s65, s19
	v_lshlrev_b32_e32 v128, 1, v128
	v_max_f32 v124, 0, v124
	v_max_f32 v120, 0, v120
	v_lshl_add_u64 v[158:159], s[18:19], 0, v[128:129]
	v_pk_mul_f32 v[122:123], v[122:123], v[200:201] op_sel_hi:[1,0]
	v_mul_f32_e32 v128, v120, v120
	v_max_f32 v120, 0, v125
	v_max_f32 v121, 0, v121
	v_lshl_or_b32 v148, s24, 8, v152
	v_pk_mul_f32 v[126:127], v[126:127], v[200:201] op_sel_hi:[1,0]
	v_mul_f32_e32 v125, v121, v121
	v_max_f32 v121, 0, v126
	v_max_f32 v122, 0, v122
	v_ashrrev_i32_e32 v149, 31, v148
	v_mul_f32_e32 v126, v122, v122
	v_max_f32 v122, 0, v127
	v_max_f32 v123, 0, v123
	v_lshl_add_u64 v[158:159], v[148:149], 1, v[158:159]
	v_mul_f32_e32 v120, v120, v120
	v_mul_f32_e32 v121, v121, v121
	v_mul_f32_e32 v122, v122, v122
	v_mul_f32_e32 v123, v123, v123
	v_pk_mul_f32 v[116:117], v[116:117], v[200:201] op_sel_hi:[1,0]
	v_pk_mul_f32 v[112:113], v[112:113], v[200:201] op_sel_hi:[1,0]
	v_mul_f32_e32 v124, v124, v124
	v_cvt_pk_bf16_f32 v120, v124, v120
	v_cvt_pk_bf16_f32 v121, v121, v122
	v_cvt_pk_bf16_f32 v122, v128, v125
	v_cvt_pk_bf16_f32 v123, v126, v123
	ds_write_b128 v154, v[120:123]
	ds_read_b128 v[248:251], v187
	s_nop 1
	v_max_f32 v116, 0, v116
	v_max_f32 v112, 0, v112
	v_pk_mul_f32 v[114:115], v[114:115], v[200:201] op_sel_hi:[1,0]
	v_pk_mul_f32 v[118:119], v[118:119], v[200:201] op_sel_hi:[1,0]
	v_mul_f32_e32 v120, v112, v112
	v_max_f32 v112, 0, v117
	v_max_f32 v113, 0, v113
	v_mul_f32_e32 v116, v116, v116
	v_mul_f32_e32 v117, v113, v113
	v_max_f32 v113, 0, v118
	v_max_f32 v114, 0, v114
	v_mul_f32_e32 v112, v112, v112
	v_mul_f32_e32 v118, v114, v114
	v_max_f32 v114, 0, v119
	v_max_f32 v115, 0, v115
	v_mul_f32_e32 v113, v113, v113
	v_mul_f32_e32 v114, v114, v114
	v_mul_f32_e32 v115, v115, v115
	v_cvt_pk_bf16_f32 v112, v116, v112
	v_cvt_pk_bf16_f32 v113, v113, v114
	v_cvt_pk_bf16_f32 v114, v120, v117
	v_cvt_pk_bf16_f32 v115, v118, v115
	s_waitcnt lgkmcnt(0)
	global_store_dwordx4 v[158:159], v[248:251], off
	ds_write_b128 v154, v[112:115]
	ds_read_b128 v[248:251], v187
	s_nop 1
	s_nop 0
	s_nop 0
	v_or_b32_e32 v112, 16, v150
	s_nop 0
.LBB0_42:
	s_nop 0
	v_pk_mul_f32 v[108:109], v[108:109], v[202:203] op_sel_hi:[1,0]
	v_pk_mul_f32 v[104:105], v[104:105], v[202:203] op_sel_hi:[1,0]
	v_and_b32_e32 v112, 0x7df, v112
	v_max_f32 v108, 0, v108
	v_max_f32 v104, 0, v104
	v_mul_u32_u24_e32 v112, 0x1040, v112
	v_pk_mul_f32 v[106:107], v[106:107], v[202:203] op_sel_hi:[1,0]
	v_mul_f32_e32 v114, v104, v104
	v_max_f32 v104, 0, v109
	v_max_f32 v105, 0, v105
	v_lshlrev_b32_e32 v128, 1, v112
	v_pk_mul_f32 v[110:111], v[110:111], v[202:203] op_sel_hi:[1,0]
	v_mul_f32_e32 v109, v105, v105
	v_max_f32 v105, 0, v110
	v_max_f32 v106, 0, v106
	v_lshl_add_u64 v[112:113], s[18:19], 0, v[128:129]
	v_mul_f32_e32 v110, v106, v106
	v_max_f32 v106, 0, v111
	v_max_f32 v107, 0, v107
	v_lshl_add_u64 v[112:113], v[148:149], 1, v[112:113]
	v_mul_f32_e32 v104, v104, v104
	v_mul_f32_e32 v105, v105, v105
	v_mul_f32_e32 v106, v106, v106
	v_mul_f32_e32 v107, v107, v107
	v_pk_mul_f32 v[100:101], v[100:101], v[202:203] op_sel_hi:[1,0]
	v_pk_mul_f32 v[96:97], v[96:97], v[202:203] op_sel_hi:[1,0]
	v_mul_f32_e32 v108, v108, v108
	v_cvt_pk_bf16_f32 v104, v108, v104
	v_cvt_pk_bf16_f32 v105, v105, v106
	v_cvt_pk_bf16_f32 v106, v114, v109
	v_cvt_pk_bf16_f32 v107, v110, v107
	s_waitcnt lgkmcnt(0)
	global_store_dwordx4 v[158:159], v[248:251], off offset:256
	ds_write_b128 v154, v[104:107]
	ds_read_b128 v[248:251], v187
	s_nop 1
	v_max_f32 v100, 0, v100
	v_max_f32 v96, 0, v96
	v_pk_mul_f32 v[98:99], v[98:99], v[202:203] op_sel_hi:[1,0]
	v_pk_mul_f32 v[102:103], v[102:103], v[202:203] op_sel_hi:[1,0]
	v_mul_f32_e32 v104, v96, v96
	v_max_f32 v96, 0, v101
	v_max_f32 v97, 0, v97
	v_mul_f32_e32 v100, v100, v100
	v_mul_f32_e32 v101, v97, v97
	v_max_f32 v97, 0, v102
	v_max_f32 v98, 0, v98
	v_mul_f32_e32 v96, v96, v96
	v_mul_f32_e32 v102, v98, v98
	v_max_f32 v98, 0, v103
	v_mul_f32_e32 v97, v97, v97
	v_mul_f32_e32 v98, v98, v98
	v_max_f32 v99, 0, v99
	v_cvt_pk_bf16_f32 v96, v100, v96
	v_cvt_pk_bf16_f32 v97, v97, v98
	v_cvt_pk_bf16_f32 v98, v104, v101
	v_or_b32_e32 v100, 32, v150
	v_mul_f32_e32 v99, v99, v99
	v_cvt_pk_bf16_f32 v99, v102, v99
	s_waitcnt lgkmcnt(0)
	global_store_dwordx4 v[112:113], v[248:251], off
	ds_write_b128 v154, v[96:99]
	ds_read_b128 v[248:251], v187
	s_nop 1
	s_nop 0
	s_nop 0
	s_nop 0
	s_nop 0
	s_nop 0
; __device__ __forceinline__ unsigned cvt_pk_bf16(float lo, float hi) { unsigned r; asm volatile("v_cvt_pk_bf16_f32 %0, %1, %2" : "=v"(r) : "v"(lo), "v"(hi)); return r; }
; __device__ __forceinline__ float relu_sq(float x) { float r; asm volatile("v_max_f32 %0, 0, %1" : "=v"(r) : "v"(x)); return r * r; }
;     __device__ __forceinline__ void operator()(const f32x4 (&acc)[2][2][4][2], const Unit& u, int wr, int wc, int fr, int fq) const {
;         const int row0 = u.pm * BM + wr * 64 + fr; const int col0 = u.pn * BM + wc * 32 + 8 * fq;
; #pragma unroll
;         for (int ai = 0; ai < 2; ++ai)
; #pragma unroll
;             for (int m = 0; m < 4; ++m) { const int row_ = row0 + ai * HALF + m * 16; bf16_t* rowp = O + (size_t)(row_ >> 11) * gs + (size_t)(row_ & 2047) * ldc + col0; const float sc = rs ? rs[row0 + ai * HALF + m * 16] : 1.f;
; #pragma unroll
;                 for (int bj = 0; bj < 2; ++bj) { f32x4 v0 = acc[ai][bj][m][0] * sc, v1 = acc[ai][bj][m][1] * sc;
;                     if (ACT == 1) {
; #pragma unroll
;                         for (int e = 0; e < 4; ++e) { v0[e] = relu_sq(v0[e]); v1[e] = relu_sq(v1[e]); } }
;                     u32x4 w; w.x = cvt_pk_bf16(v0[0], v0[1]); w.y = cvt_pk_bf16(v0[2], v0[3]); w.z = cvt_pk_bf16(v1[0], v1[1]); w.w = cvt_pk_bf16(v1[2], v1[3]);
;                     *(u32x4*)(rowp + bj * HALF) = w; } }
.LBB0_44:
	v_and_b32_e32 v97, 0x7ef, v100
	s_nop 0
	v_pk_mul_f32 v[92:93], v[92:93], v[204:205] op_sel_hi:[1,0]
	v_pk_mul_f32 v[88:89], v[88:89], v[204:205] op_sel_hi:[1,0]
	v_mul_u32_u24_e32 v97, 0x1040, v97
	v_max_f32 v92, 0, v92
	v_max_f32 v88, 0, v88
	v_lshlrev_b32_e32 v128, 1, v97
	v_pk_mul_f32 v[90:91], v[90:91], v[204:205] op_sel_hi:[1,0]
	v_mul_f32_e32 v97, v88, v88
	v_max_f32 v88, 0, v93
	v_max_f32 v89, 0, v89
	v_pk_mul_f32 v[94:95], v[94:95], v[204:205] op_sel_hi:[1,0]
	v_mul_f32_e32 v93, v89, v89
	v_max_f32 v89, 0, v94
	v_max_f32 v90, 0, v90
	v_lshl_add_u64 v[100:101], s[18:19], 0, v[128:129]
	v_mul_f32_e32 v94, v90, v90
	v_max_f32 v90, 0, v95
	v_max_f32 v91, 0, v91
	v_lshl_add_u64 v[100:101], v[148:149], 1, v[100:101]
	v_mul_f32_e32 v88, v88, v88
	v_mul_f32_e32 v89, v89, v89
	v_mul_f32_e32 v90, v90, v90
	v_mul_f32_e32 v91, v91, v91
	v_pk_mul_f32 v[84:85], v[84:85], v[204:205] op_sel_hi:[1,0]
	v_pk_mul_f32 v[80:81], v[80:81], v[204:205] op_sel_hi:[1,0]
	v_mul_f32_e32 v92, v92, v92
	v_cvt_pk_bf16_f32 v88, v92, v88
	v_cvt_pk_bf16_f32 v89, v89, v90
	v_cvt_pk_bf16_f32 v90, v97, v93
	v_cvt_pk_bf16_f32 v91, v94, v91
	s_waitcnt lgkmcnt(0)
	global_store_dwordx4 v[112:113], v[248:251], off offset:256
	ds_write_b128 v154, v[88:91]
	ds_read_b128 v[248:251], v187
	s_nop 1
	v_max_f32 v84, 0, v84
	v_max_f32 v80, 0, v80
	v_pk_mul_f32 v[82:83], v[82:83], v[204:205] op_sel_hi:[1,0]
	v_pk_mul_f32 v[86:87], v[86:87], v[204:205] op_sel_hi:[1,0]
	v_mul_f32_e32 v88, v80, v80
	v_max_f32 v80, 0, v85
	v_max_f32 v81, 0, v81
	v_mul_f32_e32 v84, v84, v84
	v_mul_f32_e32 v85, v81, v81
	v_max_f32 v81, 0, v86
	v_max_f32 v82, 0, v82
	v_mul_f32_e32 v80, v80, v80
	v_mul_f32_e32 v86, v82, v82
	v_max_f32 v82, 0, v87
	v_max_f32 v83, 0, v83
	v_mul_f32_e32 v81, v81, v81
	v_mul_f32_e32 v82, v82, v82
	v_mul_f32_e32 v83, v83, v83
	v_cvt_pk_bf16_f32 v80, v84, v80
	v_cvt_pk_bf16_f32 v81, v81, v82
	v_cvt_pk_bf16_f32 v82, v88, v85
	v_cvt_pk_bf16_f32 v83, v86, v83
	s_waitcnt lgkmcnt(0)
	global_store_dwordx4 v[100:101], v[248:251], off
	ds_write_b128 v154, v[80:83]
	ds_read_b128 v[248:251], v187
	s_nop 1
	s_nop 0
	s_nop 0
	v_or_b32_e32 v80, 48, v150
	s_nop 0
.LBB0_46:
	s_nop 0
	v_pk_mul_f32 v[76:77], v[76:77], v[206:207] op_sel_hi:[1,0]
	v_pk_mul_f32 v[72:73], v[72:73], v[206:207] op_sel_hi:[1,0]
	v_and_b32_e32 v80, 0x7ff, v80
	v_max_f32 v76, 0, v76
	v_max_f32 v72, 0, v72
	v_mul_u32_u24_e32 v80, 0x1040, v80
	v_pk_mul_f32 v[74:75], v[74:75], v[206:207] op_sel_hi:[1,0]
	v_mul_f32_e32 v82, v72, v72
	v_max_f32 v72, 0, v77
	v_max_f32 v73, 0, v73
	v_lshlrev_b32_e32 v128, 1, v80
	v_pk_mul_f32 v[78:79], v[78:79], v[206:207] op_sel_hi:[1,0]
	v_mul_f32_e32 v77, v73, v73
	v_max_f32 v73, 0, v78
	v_max_f32 v74, 0, v74
	v_lshl_add_u64 v[80:81], s[18:19], 0, v[128:129]
	v_mul_f32_e32 v78, v74, v74
	v_max_f32 v74, 0, v79
	v_max_f32 v75, 0, v75
	v_lshl_add_u64 v[80:81], v[148:149], 1, v[80:81]
	v_mul_f32_e32 v72, v72, v72
	v_mul_f32_e32 v73, v73, v73
	v_mul_f32_e32 v74, v74, v74
	v_mul_f32_e32 v75, v75, v75
	v_pk_mul_f32 v[68:69], v[68:69], v[206:207] op_sel_hi:[1,0]
	v_pk_mul_f32 v[64:65], v[64:65], v[206:207] op_sel_hi:[1,0]
	v_mul_f32_e32 v76, v76, v76
	v_cvt_pk_bf16_f32 v72, v76, v72
	v_cvt_pk_bf16_f32 v73, v73, v74
	v_cvt_pk_bf16_f32 v74, v82, v77
	v_cvt_pk_bf16_f32 v75, v78, v75
	s_waitcnt lgkmcnt(0)
	global_store_dwordx4 v[100:101], v[248:251], off offset:256
	ds_write_b128 v154, v[72:75]
	ds_read_b128 v[248:251], v187
	s_nop 1
	v_max_f32 v68, 0, v68
	v_max_f32 v64, 0, v64
	v_pk_mul_f32 v[66:67], v[66:67], v[206:207] op_sel_hi:[1,0]
	v_pk_mul_f32 v[70:71], v[70:71], v[206:207] op_sel_hi:[1,0]
	v_mul_f32_e32 v72, v64, v64
	v_max_f32 v64, 0, v69
	v_max_f32 v65, 0, v65
	v_mul_f32_e32 v68, v68, v68
	v_mul_f32_e32 v69, v65, v65
	v_max_f32 v65, 0, v70
	v_max_f32 v66, 0, v66
	v_mul_f32_e32 v64, v64, v64
	v_mul_f32_e32 v70, v66, v66
	v_max_f32 v66, 0, v71
	v_mul_f32_e32 v65, v65, v65
	v_mul_f32_e32 v66, v66, v66
	v_max_f32 v67, 0, v67
	v_cvt_pk_bf16_f32 v64, v68, v64
	v_cvt_pk_bf16_f32 v65, v65, v66
	v_cvt_pk_bf16_f32 v66, v72, v69
	s_nop 0
	v_mul_f32_e32 v67, v67, v67
	v_cvt_pk_bf16_f32 v67, v70, v67
	s_waitcnt lgkmcnt(0)
	global_store_dwordx4 v[80:81], v[248:251], off
	ds_write_b128 v154, v[64:67]
	ds_read_b128 v[248:251], v187
	s_nop 1
	v_add_u32_e32 v70, 0x80, v150
	s_nop 0
	s_nop 0
	s_nop 0
.LBB0_48:
	v_ashrrev_i32_e32 v67, 11, v70
	v_mov_b64_e32 v[64:65], s[64:65]
	s_mov_b32 s13, 0x1040000
	v_mad_i64_i32 v[64:65], s[18:19], v67, s13, v[64:65]
	v_and_b32_e32 v67, 0x7cf, v70
	s_nop 0
	v_pk_mul_f32 v[60:61], v[60:61], v[208:209] op_sel_hi:[1,0]
	v_pk_mul_f32 v[56:57], v[56:57], v[208:209] op_sel_hi:[1,0]
	v_mul_u32_u24_e32 v67, 0x1040, v67
	v_max_f32 v60, 0, v60
	v_max_f32 v56, 0, v56
	v_lshlrev_b32_e32 v128, 1, v67
	v_pk_mul_f32 v[58:59], v[58:59], v[208:209] op_sel_hi:[1,0]
	v_mul_f32_e32 v67, v56, v56
	v_max_f32 v56, 0, v61
	v_max_f32 v57, 0, v57
	v_pk_mul_f32 v[62:63], v[62:63], v[208:209] op_sel_hi:[1,0]
	v_mul_f32_e32 v61, v57, v57
	v_max_f32 v57, 0, v62
	v_max_f32 v58, 0, v58
	v_lshl_add_u64 v[70:71], v[64:65], 0, v[128:129]
	v_mul_f32_e32 v62, v58, v58
	v_max_f32 v58, 0, v63
	v_max_f32 v59, 0, v59
	v_lshl_add_u64 v[70:71], v[148:149], 1, v[70:71]
	v_mul_f32_e32 v56, v56, v56
	v_mul_f32_e32 v57, v57, v57
	v_mul_f32_e32 v58, v58, v58
	v_mul_f32_e32 v59, v59, v59
	v_pk_mul_f32 v[52:53], v[52:53], v[208:209] op_sel_hi:[1,0]
	v_pk_mul_f32 v[48:49], v[48:49], v[208:209] op_sel_hi:[1,0]
	v_mul_f32_e32 v60, v60, v60
	v_cvt_pk_bf16_f32 v56, v60, v56
	v_cvt_pk_bf16_f32 v57, v57, v58
	v_cvt_pk_bf16_f32 v58, v67, v61
	v_cvt_pk_bf16_f32 v59, v62, v59
	s_waitcnt lgkmcnt(0)
	global_store_dwordx4 v[80:81], v[248:251], off offset:256
	ds_write_b128 v154, v[56:59]
	ds_read_b128 v[248:251], v187
	s_nop 1
	v_max_f32 v52, 0, v52
	v_max_f32 v48, 0, v48
	v_pk_mul_f32 v[50:51], v[50:51], v[208:209] op_sel_hi:[1,0]
	v_pk_mul_f32 v[54:55], v[54:55], v[208:209] op_sel_hi:[1,0]
	v_mul_f32_e32 v56, v48, v48
	v_max_f32 v48, 0, v53
	v_max_f32 v49, 0, v49
	v_mul_f32_e32 v52, v52, v52
	v_mul_f32_e32 v53, v49, v49
	v_max_f32 v49, 0, v54
	v_max_f32 v50, 0, v50
	v_mul_f32_e32 v48, v48, v48
	v_mul_f32_e32 v54, v50, v50
	v_max_f32 v50, 0, v55
	v_max_f32 v51, 0, v51
	v_mul_f32_e32 v49, v49, v49
	v_mul_f32_e32 v50, v50, v50
	v_mul_f32_e32 v51, v51, v51
	v_cvt_pk_bf16_f32 v48, v52, v48
	v_cvt_pk_bf16_f32 v49, v49, v50
	v_cvt_pk_bf16_f32 v50, v56, v53
	v_cvt_pk_bf16_f32 v51, v54, v51
	s_waitcnt lgkmcnt(0)
	global_store_dwordx4 v[70:71], v[248:251], off
	ds_write_b128 v154, v[48:51]
	ds_read_b128 v[248:251], v187
	s_nop 1
	s_nop 0
	s_nop 0
	v_add_u32_e32 v48, 0x90, v150
	s_nop 0
; __device__ __forceinline__ unsigned cvt_pk_bf16(float lo, float hi) { unsigned r; asm volatile("v_cvt_pk_bf16_f32 %0, %1, %2" : "=v"(r) : "v"(lo), "v"(hi)); return r; }
; __device__ __forceinline__ float relu_sq(float x) { float r; asm volatile("v_max_f32 %0, 0, %1" : "=v"(r) : "v"(x)); return r * r; }
;     __device__ __forceinline__ void operator()(const f32x4 (&acc)[2][2][4][2], const Unit& u, int wr, int wc, int fr, int fq) const {
;     ...
;             for (int m = 0; m < 4; ++m) { const int row_ = row0 + ai * HALF + m * 16; bf16_t* rowp = O + (size_t)(row_ >> 11) * gs + (size_t)(row_ & 2047) * ldc + col0; const float sc = rs ? rs[row0 + ai * HALF + m * 16] : 1.f;
; #pragma unroll
;                 for (int bj = 0; bj < 2; ++bj) { f32x4 v0 = acc[ai][bj][m][0] * sc, v1 = acc[ai][bj][m][1] * sc;
;                     if (ACT == 1) {
; #pragma unroll
;                         for (int e = 0; e < 4; ++e) { v0[e] = relu_sq(v0[e]); v1[e] = relu_sq(v1[e]); } }
;                     u32x4 w; w.x = cvt_pk_bf16(v0[0], v0[1]); w.y = cvt_pk_bf16(v0[2], v0[3]); w.z = cvt_pk_bf16(v1[0], v1[1]); w.w = cvt_pk_bf16(v1[2], v1[3]);
;                     *(u32x4*)(rowp + bj * HALF) = w; } }
.LBB0_50:
	s_nop 0
	v_pk_mul_f32 v[44:45], v[44:45], v[210:211] op_sel_hi:[1,0]
	v_pk_mul_f32 v[40:41], v[40:41], v[210:211] op_sel_hi:[1,0]
	v_and_b32_e32 v48, 0x7df, v48
	v_max_f32 v44, 0, v44
	v_max_f32 v40, 0, v40
	v_mul_u32_u24_e32 v48, 0x1040, v48
	v_pk_mul_f32 v[42:43], v[42:43], v[210:211] op_sel_hi:[1,0]
	v_mul_f32_e32 v50, v40, v40
	v_max_f32 v40, 0, v45
	v_max_f32 v41, 0, v41
	v_lshlrev_b32_e32 v128, 1, v48
	v_pk_mul_f32 v[46:47], v[46:47], v[210:211] op_sel_hi:[1,0]
	v_mul_f32_e32 v45, v41, v41
	v_max_f32 v41, 0, v46
	v_max_f32 v42, 0, v42
	v_lshl_add_u64 v[48:49], v[64:65], 0, v[128:129]
	v_mul_f32_e32 v46, v42, v42
	v_max_f32 v42, 0, v47
	v_max_f32 v43, 0, v43
	v_lshl_add_u64 v[48:49], v[148:149], 1, v[48:49]
	v_mul_f32_e32 v40, v40, v40
	v_mul_f32_e32 v41, v41, v41
	v_mul_f32_e32 v42, v42, v42
	v_mul_f32_e32 v43, v43, v43
	v_pk_mul_f32 v[36:37], v[36:37], v[210:211] op_sel_hi:[1,0]
	v_pk_mul_f32 v[32:33], v[32:33], v[210:211] op_sel_hi:[1,0]
	v_mul_f32_e32 v44, v44, v44
	v_cvt_pk_bf16_f32 v40, v44, v40
	v_cvt_pk_bf16_f32 v41, v41, v42
	v_cvt_pk_bf16_f32 v42, v50, v45
	v_cvt_pk_bf16_f32 v43, v46, v43
	s_waitcnt lgkmcnt(0)
	global_store_dwordx4 v[70:71], v[248:251], off offset:256
	ds_write_b128 v154, v[40:43]
	ds_read_b128 v[248:251], v187
	s_nop 1
	v_max_f32 v36, 0, v36
	v_max_f32 v32, 0, v32
	v_pk_mul_f32 v[34:35], v[34:35], v[210:211] op_sel_hi:[1,0]
	v_pk_mul_f32 v[38:39], v[38:39], v[210:211] op_sel_hi:[1,0]
	v_mul_f32_e32 v40, v32, v32
	v_max_f32 v32, 0, v37
	v_max_f32 v33, 0, v33
	v_mul_f32_e32 v36, v36, v36
	v_mul_f32_e32 v37, v33, v33
	v_max_f32 v33, 0, v38
	v_max_f32 v34, 0, v34
	v_mul_f32_e32 v32, v32, v32
	v_mul_f32_e32 v38, v34, v34
	v_max_f32 v34, 0, v39
	v_mul_f32_e32 v33, v33, v33
	v_mul_f32_e32 v34, v34, v34
	v_max_f32 v35, 0, v35
	v_cvt_pk_bf16_f32 v32, v36, v32
	v_cvt_pk_bf16_f32 v33, v33, v34
	v_cvt_pk_bf16_f32 v34, v40, v37
	v_add_u32_e32 v36, 0xa0, v150
	v_mul_f32_e32 v35, v35, v35
	v_cvt_pk_bf16_f32 v35, v38, v35
	s_waitcnt lgkmcnt(0)
	global_store_dwordx4 v[48:49], v[248:251], off
	ds_write_b128 v154, v[32:35]
	ds_read_b128 v[248:251], v187
	s_nop 1
	s_nop 0
	s_nop 0
	s_nop 0
	s_nop 0
	s_nop 0
.LBB0_52:
	v_and_b32_e32 v33, 0x7ef, v36
	s_nop 0
	v_pk_mul_f32 v[28:29], v[28:29], v[212:213] op_sel_hi:[1,0]
	v_pk_mul_f32 v[24:25], v[24:25], v[212:213] op_sel_hi:[1,0]
	v_mul_u32_u24_e32 v33, 0x1040, v33
	v_max_f32 v28, 0, v28
	v_max_f32 v24, 0, v24
	v_lshlrev_b32_e32 v128, 1, v33
	v_pk_mul_f32 v[26:27], v[26:27], v[212:213] op_sel_hi:[1,0]
	v_mul_f32_e32 v33, v24, v24
	v_max_f32 v24, 0, v29
	v_max_f32 v25, 0, v25
	v_pk_mul_f32 v[30:31], v[30:31], v[212:213] op_sel_hi:[1,0]
	v_mul_f32_e32 v29, v25, v25
	v_max_f32 v25, 0, v30
	v_max_f32 v26, 0, v26
	v_lshl_add_u64 v[36:37], v[64:65], 0, v[128:129]
	v_mul_f32_e32 v30, v26, v26
	v_max_f32 v26, 0, v31
	v_max_f32 v27, 0, v27
	v_lshl_add_u64 v[36:37], v[148:149], 1, v[36:37]
	v_mul_f32_e32 v24, v24, v24
	v_mul_f32_e32 v25, v25, v25
	v_mul_f32_e32 v26, v26, v26
	v_mul_f32_e32 v27, v27, v27
	v_pk_mul_f32 v[20:21], v[20:21], v[212:213] op_sel_hi:[1,0]
	v_pk_mul_f32 v[16:17], v[16:17], v[212:213] op_sel_hi:[1,0]
	v_mul_f32_e32 v28, v28, v28
	v_cvt_pk_bf16_f32 v24, v28, v24
	v_cvt_pk_bf16_f32 v25, v25, v26
	v_cvt_pk_bf16_f32 v26, v33, v29
	v_cvt_pk_bf16_f32 v27, v30, v27
	s_waitcnt lgkmcnt(0)
	global_store_dwordx4 v[48:49], v[248:251], off offset:256
	ds_write_b128 v154, v[24:27]
	ds_read_b128 v[248:251], v187
	s_nop 1
	v_max_f32 v20, 0, v20
	v_max_f32 v16, 0, v16
	v_pk_mul_f32 v[18:19], v[18:19], v[212:213] op_sel_hi:[1,0]
	v_pk_mul_f32 v[22:23], v[22:23], v[212:213] op_sel_hi:[1,0]
	v_mul_f32_e32 v24, v16, v16
	v_max_f32 v16, 0, v21
	v_max_f32 v17, 0, v17
	v_mul_f32_e32 v20, v20, v20
	v_mul_f32_e32 v21, v17, v17
	v_max_f32 v17, 0, v22
	v_max_f32 v18, 0, v18
	v_mul_f32_e32 v16, v16, v16
	v_mul_f32_e32 v22, v18, v18
	v_max_f32 v18, 0, v23
	v_max_f32 v19, 0, v19
	v_mul_f32_e32 v17, v17, v17
	v_mul_f32_e32 v18, v18, v18
	v_mul_f32_e32 v19, v19, v19
	v_cvt_pk_bf16_f32 v16, v20, v16
	v_cvt_pk_bf16_f32 v17, v17, v18
	v_cvt_pk_bf16_f32 v18, v24, v21
	v_cvt_pk_bf16_f32 v19, v22, v19
	s_waitcnt lgkmcnt(0)
	global_store_dwordx4 v[36:37], v[248:251], off
	ds_write_b128 v154, v[16:19]
	ds_read_b128 v[248:251], v187
	s_nop 1
	s_nop 0
	s_nop 0
	v_add_u32_e32 v16, 0xb0, v150
	s_nop 0
.LBB0_54:
	s_nop 0
	v_pk_mul_f32 v[12:13], v[12:13], v[214:215] op_sel_hi:[1,0]
	v_pk_mul_f32 v[8:9], v[8:9], v[214:215] op_sel_hi:[1,0]
	v_and_b32_e32 v16, 0x7ff, v16
	v_max_f32 v12, 0, v12
	v_max_f32 v8, 0, v8
	v_mul_u32_u24_e32 v16, 0x1040, v16
	v_pk_mul_f32 v[10:11], v[10:11], v[214:215] op_sel_hi:[1,0]
	v_mul_f32_e32 v18, v8, v8
	v_max_f32 v8, 0, v13
	v_max_f32 v9, 0, v9
	v_lshlrev_b32_e32 v128, 1, v16
	v_pk_mul_f32 v[14:15], v[14:15], v[214:215] op_sel_hi:[1,0]
	v_mul_f32_e32 v13, v9, v9
	v_max_f32 v9, 0, v14
	v_max_f32 v10, 0, v10
	v_lshl_add_u64 v[16:17], v[64:65], 0, v[128:129]
	v_mul_f32_e32 v14, v10, v10
	v_max_f32 v10, 0, v15
	v_max_f32 v11, 0, v11
	v_lshl_add_u64 v[16:17], v[148:149], 1, v[16:17]
	v_mul_f32_e32 v8, v8, v8
	v_mul_f32_e32 v9, v9, v9
	v_mul_f32_e32 v10, v10, v10
	v_mul_f32_e32 v11, v11, v11
	v_pk_mul_f32 v[4:5], v[4:5], v[214:215] op_sel_hi:[1,0]
	v_pk_mul_f32 v[0:1], v[0:1], v[214:215] op_sel_hi:[1,0]
	v_mul_f32_e32 v12, v12, v12
	v_cvt_pk_bf16_f32 v8, v12, v8
	v_cvt_pk_bf16_f32 v9, v9, v10
	v_cvt_pk_bf16_f32 v10, v18, v13
	v_cvt_pk_bf16_f32 v11, v14, v11
	s_waitcnt lgkmcnt(0)
	global_store_dwordx4 v[36:37], v[248:251], off offset:256
	ds_write_b128 v154, v[8:11]
	ds_read_b128 v[248:251], v187
	s_nop 1
	v_max_f32 v4, 0, v4
	v_max_f32 v0, 0, v0
	v_pk_mul_f32 v[2:3], v[2:3], v[214:215] op_sel_hi:[1,0]
	v_pk_mul_f32 v[6:7], v[6:7], v[214:215] op_sel_hi:[1,0]
	v_mul_f32_e32 v8, v0, v0
	v_max_f32 v0, 0, v5
	v_max_f32 v1, 0, v1
	s_andn2_b64 vcc, exec, s[6:7]
	v_mul_f32_e32 v5, v1, v1
	v_max_f32 v1, 0, v6
	v_max_f32 v2, 0, v2
	v_mul_f32_e32 v0, v0, v0
	v_mul_f32_e32 v6, v2, v2
	v_max_f32 v2, 0, v7
	v_max_f32 v3, 0, v3
	v_mul_f32_e32 v1, v1, v1
	v_mul_f32_e32 v2, v2, v2
	v_mul_f32_e32 v3, v3, v3
	s_mov_b64 s[6:7], -1
	v_mul_f32_e32 v4, v4, v4
	v_cvt_pk_bf16_f32 v0, v4, v0
	v_cvt_pk_bf16_f32 v1, v1, v2
	v_cvt_pk_bf16_f32 v2, v8, v5
	v_cvt_pk_bf16_f32 v3, v6, v3
	s_waitcnt lgkmcnt(0)
	global_store_dwordx4 v[16:17], v[248:251], off
	ds_write_b128 v154, v[0:3]
	ds_read_b128 v[248:251], v187
	s_waitcnt lgkmcnt(0)
	global_store_dwordx4 v[16:17], v[248:251], off offset:256
	s_cbranch_vccnz .LBB0_27
	s_andn2_b64 vcc, exec, s[4:5]
	s_cbranch_vccnz .LBB0_26
	s_barrier
	s_branch .LBB0_26

; __device__ __forceinline__ unsigned cvt_pk_bf16(float lo, float hi) { unsigned r; asm volatile("v_cvt_pk_bf16_f32 %0, %1, %2" : "=v"(r) : "v"(lo), "v"(hi)); return r; }
; __device__ __forceinline__ float relu_sq(float x) { float r; asm volatile("v_max_f32 %0, 0, %1" : "=v"(r) : "v"(x)); return r * r; }
;     __device__ __forceinline__ void operator()(const f32x4 (&acc)[2][2][4][2], const Unit& u, int wr, int wc, int fr, int fq) const {
;         const int row0 = u.pm * BM + wr * 64 + fr; const int col0 = u.pn * BM + wc * 32 + 8 * fq;
; #pragma unroll
;         for (int ai = 0; ai < 2; ++ai)
; #pragma unroll
;             for (int m = 0; m < 4; ++m) { const int row_ = row0 + ai * HALF + m * 16; bf16_t* rowp = O + (size_t)(row_ >> 11) * gs + (size_t)(row_ & 2047) * ldc + col0; const float sc = rs ? rs[row0 + ai * HALF + m * 16] : 1.f;
; #pragma unroll
;                 for (int bj = 0; bj < 2; ++bj) { f32x4 v0 = acc[ai][bj][m][0] * sc, v1 = acc[ai][bj][m][1] * sc;
;                     if (ACT == 1) {
; #pragma unroll
;                         for (int e = 0; e < 4; ++e) { v0[e] = relu_sq(v0[e]); v1[e] = relu_sq(v1[e]); } }
;                     u32x4 w; w.x = cvt_pk_bf16(v0[0], v0[1]); w.y = cvt_pk_bf16(v0[2], v0[3]); w.z = cvt_pk_bf16(v1[0], v1[1]); w.w = cvt_pk_bf16(v1[2], v1[3]);
;                     *(u32x4*)(rowp + bj * HALF) = w; } }
.Lplepi_go:
	global_load_dword v255, v129, s[100:101] sc1
	v_bfe_u32 v152, v186, 2, 4
	v_or_b32_e32 v150, s41, v152
	v_and_b32_e32 v187, 63, v186
	v_lshlrev_b32_e32 v187, 4, v187
	v_lshrrev_b32_e32 v152, 6, v186
	v_lshl_add_u32 v187, v152, 10, v187
	v_add_u32_e32 v187, 0x20000, v187
	v_and_b32_e32 v154, 15, v186
	v_bfe_u32 v148, v154, 1, 2
	v_bfe_u32 v149, v186, 4, 2
	v_xor_b32_e32 v148, v148, v149
	v_lshlrev_b32_e32 v148, 4, v148
	v_lshl_or_b32 v154, v154, 6, v148
	v_lshl_add_u32 v154, v152, 10, v154
	v_add_u32_e32 v154, 0x20000, v154
	v_bfe_u32 v152, v186, 3, 2
	v_and_b32_e32 v148, 3, v186
	v_xor_b32_e32 v152, v152, v148
	v_lshlrev_b32_e32 v152, 3, v152
	v_and_b32_e32 v148, 0xffffffe7, v156
	v_or_b32_e32 v152, v152, v148
.LBB0_473:
	v_bitop3_b32 v128, v150, v184, v150 bitop3:0xc8
	s_ashr_i32 s41, s41, 11
	s_mul_hi_i32 s43, s26, s41
	s_mul_i32 s42, s26, s41
	s_lshl_b64 s[42:43], s[42:43], 1
	v_lshl_or_b32 v148, s88, 8, v152
	s_add_u32 s88, s12, s42
	v_mul_u32_u24_e32 v128, s39, v128
	s_addc_u32 s89, s13, s43
	v_lshlrev_b32_e32 v128, 1, v128
	v_ashrrev_i32_e32 v149, 31, v148
	v_lshl_add_u64 v[158:159], s[88:89], 0, v[128:129]
	v_lshl_add_u64 v[158:159], v[148:149], 1, v[158:159]
	s_waitcnt vmcnt(0)
	v_pk_mul_f32 v[126:127], v[126:127], v[200:201] op_sel_hi:[1,0]
	v_pk_mul_f32 v[124:125], v[124:125], v[200:201] op_sel_hi:[1,0]
	v_pk_mul_f32 v[160:161], v[122:123], v[200:201] op_sel_hi:[1,0]
	v_pk_mul_f32 v[122:123], v[120:121], v[200:201] op_sel_hi:[1,0]
	v_cvt_pk_bf16_f32 v120, v124, v125
	v_cvt_pk_bf16_f32 v121, v126, v127
	s_nop 0
	v_cvt_pk_bf16_f32 v122, v122, v123
	v_cvt_pk_bf16_f32 v123, v160, v161
	ds_write_b128 v154, v[120:123]
	s_waitcnt lgkmcnt(0)
	ds_read_b128 v[120:123], v187
	s_waitcnt lgkmcnt(0)
	global_store_dwordx4 v[158:159], v[120:123], off
	v_pk_mul_f32 v[118:119], v[118:119], v[200:201] op_sel_hi:[1,0]
	v_pk_mul_f32 v[116:117], v[116:117], v[200:201] op_sel_hi:[1,0]
	v_pk_mul_f32 v[120:121], v[114:115], v[200:201] op_sel_hi:[1,0]
	v_pk_mul_f32 v[114:115], v[112:113], v[200:201] op_sel_hi:[1,0]
	v_cvt_pk_bf16_f32 v112, v116, v117
	v_cvt_pk_bf16_f32 v113, v118, v119
	s_nop 0
	v_cvt_pk_bf16_f32 v114, v114, v115
	v_cvt_pk_bf16_f32 v115, v120, v121
	ds_write_b128 v154, v[112:115]
	s_waitcnt lgkmcnt(0)
	ds_read_b128 v[112:115], v187
	s_waitcnt lgkmcnt(0)
	global_store_dwordx4 v[158:159], v[112:115], off offset:256
	s_nop 0
.LBB0_475:
	s_movk_i32 s41, 0x7df
	v_bitop3_b32 v112, v150, s41, 16 bitop3:0xc8
	v_mul_u32_u24_e32 v112, s39, v112
	v_lshlrev_b32_e32 v128, 1, v112
	v_lshl_add_u64 v[112:113], s[88:89], 0, v[128:129]
	v_lshl_add_u64 v[112:113], v[148:149], 1, v[112:113]
	s_nop 0
	v_pk_mul_f32 v[110:111], v[110:111], v[202:203] op_sel_hi:[1,0]
	v_pk_mul_f32 v[108:109], v[108:109], v[202:203] op_sel_hi:[1,0]
	v_pk_mul_f32 v[114:115], v[106:107], v[202:203] op_sel_hi:[1,0]
	v_pk_mul_f32 v[106:107], v[104:105], v[202:203] op_sel_hi:[1,0]
	v_cvt_pk_bf16_f32 v104, v108, v109
	v_cvt_pk_bf16_f32 v105, v110, v111
	v_pk_mul_f32 v[102:103], v[102:103], v[202:203] op_sel_hi:[1,0]
	v_cvt_pk_bf16_f32 v106, v106, v107
	v_cvt_pk_bf16_f32 v107, v114, v115
	ds_write_b128 v154, v[104:107]
	s_waitcnt lgkmcnt(0)
	ds_read_b128 v[104:107], v187
	s_waitcnt lgkmcnt(0)
	global_store_dwordx4 v[112:113], v[104:107], off
	v_pk_mul_f32 v[100:101], v[100:101], v[202:203] op_sel_hi:[1,0]
	s_nop 0
	v_pk_mul_f32 v[104:105], v[98:99], v[202:203] op_sel_hi:[1,0]
	v_pk_mul_f32 v[98:99], v[96:97], v[202:203] op_sel_hi:[1,0]
	v_cvt_pk_bf16_f32 v96, v100, v101
	v_cvt_pk_bf16_f32 v97, v102, v103
	s_nop 0
	v_cvt_pk_bf16_f32 v98, v98, v99
	v_cvt_pk_bf16_f32 v99, v104, v105
	ds_write_b128 v154, v[96:99]
	s_waitcnt lgkmcnt(0)
	ds_read_b128 v[96:99], v187
	s_waitcnt lgkmcnt(0)
	global_store_dwordx4 v[112:113], v[96:99], off offset:256
	s_nop 1
	s_nop 0
	s_nop 0
	s_nop 0
.LBB0_477:
	v_bitop3_b32 v97, v150, s51, 32 bitop3:0xc8
	v_mul_u32_u24_e32 v97, s39, v97
	v_lshlrev_b32_e32 v128, 1, v97
	v_lshl_add_u64 v[100:101], s[88:89], 0, v[128:129]
	v_lshl_add_u64 v[100:101], v[148:149], 1, v[100:101]
	s_nop 0
	v_pk_mul_f32 v[94:95], v[94:95], v[204:205] op_sel_hi:[1,0]
	v_pk_mul_f32 v[92:93], v[92:93], v[204:205] op_sel_hi:[1,0]
	v_pk_mul_f32 v[102:103], v[90:91], v[204:205] op_sel_hi:[1,0]
	v_pk_mul_f32 v[90:91], v[88:89], v[204:205] op_sel_hi:[1,0]
	v_cvt_pk_bf16_f32 v88, v92, v93
	v_cvt_pk_bf16_f32 v89, v94, v95
	s_nop 0
	v_cvt_pk_bf16_f32 v90, v90, v91
	v_cvt_pk_bf16_f32 v91, v102, v103
	ds_write_b128 v154, v[88:91]
	s_waitcnt lgkmcnt(0)
	ds_read_b128 v[88:91], v187
	s_waitcnt lgkmcnt(0)
	global_store_dwordx4 v[100:101], v[88:91], off
	v_pk_mul_f32 v[86:87], v[86:87], v[204:205] op_sel_hi:[1,0]
	v_pk_mul_f32 v[84:85], v[84:85], v[204:205] op_sel_hi:[1,0]
	v_pk_mul_f32 v[88:89], v[82:83], v[204:205] op_sel_hi:[1,0]
	v_pk_mul_f32 v[82:83], v[80:81], v[204:205] op_sel_hi:[1,0]
	v_cvt_pk_bf16_f32 v80, v84, v85
	v_cvt_pk_bf16_f32 v81, v86, v87
	s_nop 0
	v_cvt_pk_bf16_f32 v82, v82, v83
	v_cvt_pk_bf16_f32 v83, v88, v89
	ds_write_b128 v154, v[80:83]
	s_waitcnt lgkmcnt(0)
	ds_read_b128 v[80:83], v187
	s_waitcnt lgkmcnt(0)
	global_store_dwordx4 v[100:101], v[80:83], off offset:256
	s_nop 0
; __device__ __forceinline__ unsigned cvt_pk_bf16(float lo, float hi) { unsigned r; asm volatile("v_cvt_pk_bf16_f32 %0, %1, %2" : "=v"(r) : "v"(lo), "v"(hi)); return r; }
; __device__ __forceinline__ float relu_sq(float x) { float r; asm volatile("v_max_f32 %0, 0, %1" : "=v"(r) : "v"(x)); return r * r; }
;     __device__ __forceinline__ void operator()(const f32x4 (&acc)[2][2][4][2], const Unit& u, int wr, int wc, int fr, int fq) const {
;     ...
;             for (int m = 0; m < 4; ++m) { const int row_ = row0 + ai * HALF + m * 16; bf16_t* rowp = O + (size_t)(row_ >> 11) * gs + (size_t)(row_ & 2047) * ldc + col0; const float sc = rs ? rs[row0 + ai * HALF + m * 16] : 1.f;
; #pragma unroll
;                 for (int bj = 0; bj < 2; ++bj) { f32x4 v0 = acc[ai][bj][m][0] * sc, v1 = acc[ai][bj][m][1] * sc;
;                     if (ACT == 1) {
; #pragma unroll
;                         for (int e = 0; e < 4; ++e) { v0[e] = relu_sq(v0[e]); v1[e] = relu_sq(v1[e]); } }
;                     u32x4 w; w.x = cvt_pk_bf16(v0[0], v0[1]); w.y = cvt_pk_bf16(v0[2], v0[3]); w.z = cvt_pk_bf16(v1[0], v1[1]); w.w = cvt_pk_bf16(v1[2], v1[3]);
;                     *(u32x4*)(rowp + bj * HALF) = w; } }
.LBB0_479:
	s_movk_i32 s41, 0x7ff
	v_bitop3_b32 v80, v150, s41, 48 bitop3:0xc8
	v_mul_u32_u24_e32 v80, s39, v80
	v_lshlrev_b32_e32 v128, 1, v80
	v_lshl_add_u64 v[80:81], s[88:89], 0, v[128:129]
	v_lshl_add_u64 v[80:81], v[148:149], 1, v[80:81]
	s_nop 0
	v_pk_mul_f32 v[78:79], v[78:79], v[206:207] op_sel_hi:[1,0]
	v_pk_mul_f32 v[76:77], v[76:77], v[206:207] op_sel_hi:[1,0]
	v_pk_mul_f32 v[82:83], v[74:75], v[206:207] op_sel_hi:[1,0]
	v_pk_mul_f32 v[74:75], v[72:73], v[206:207] op_sel_hi:[1,0]
	v_cvt_pk_bf16_f32 v72, v76, v77
	v_cvt_pk_bf16_f32 v73, v78, v79
	v_pk_mul_f32 v[70:71], v[70:71], v[206:207] op_sel_hi:[1,0]
	v_cvt_pk_bf16_f32 v74, v74, v75
	v_cvt_pk_bf16_f32 v75, v82, v83
	ds_write_b128 v154, v[72:75]
	s_waitcnt lgkmcnt(0)
	ds_read_b128 v[72:75], v187
	s_waitcnt lgkmcnt(0)
	global_store_dwordx4 v[80:81], v[72:75], off
	v_pk_mul_f32 v[68:69], v[68:69], v[206:207] op_sel_hi:[1,0]
	s_nop 0
	v_pk_mul_f32 v[72:73], v[66:67], v[206:207] op_sel_hi:[1,0]
	v_pk_mul_f32 v[66:67], v[64:65], v[206:207] op_sel_hi:[1,0]
	v_cvt_pk_bf16_f32 v64, v68, v69
	v_cvt_pk_bf16_f32 v65, v70, v71
	s_nop 0
	v_cvt_pk_bf16_f32 v66, v66, v67
	v_cvt_pk_bf16_f32 v67, v72, v73
	ds_write_b128 v154, v[64:67]
	s_waitcnt lgkmcnt(0)
	ds_read_b128 v[64:67], v187
	s_waitcnt lgkmcnt(0)
	global_store_dwordx4 v[80:81], v[64:67], off offset:256
	s_nop 1
	v_add_u32_e32 v64, 0x80, v150
	s_nop 0
	s_nop 0
.LBB0_481:
	v_and_b32_e32 v67, 0x7cf, v64
	v_ashrrev_i32_e32 v64, 11, v64
	v_mad_i64_i32 v[64:65], s[42:43], s26, v64, 0
	v_mul_u32_u24_e32 v67, s39, v67
	v_lshl_add_u64 v[64:65], v[64:65], 1, s[12:13]
	v_lshlrev_b32_e32 v128, 1, v67
	v_lshl_add_u64 v[70:71], v[64:65], 0, v[128:129]
	v_lshl_add_u64 v[70:71], v[148:149], 1, v[70:71]
	s_nop 0
	v_pk_mul_f32 v[62:63], v[62:63], v[208:209] op_sel_hi:[1,0]
	v_pk_mul_f32 v[60:61], v[60:61], v[208:209] op_sel_hi:[1,0]
	v_pk_mul_f32 v[72:73], v[58:59], v[208:209] op_sel_hi:[1,0]
	v_pk_mul_f32 v[58:59], v[56:57], v[208:209] op_sel_hi:[1,0]
	v_cvt_pk_bf16_f32 v56, v60, v61
	v_cvt_pk_bf16_f32 v57, v62, v63
	v_pk_mul_f32 v[52:53], v[52:53], v[208:209] op_sel_hi:[1,0]
	v_cvt_pk_bf16_f32 v58, v58, v59
	v_cvt_pk_bf16_f32 v59, v72, v73
	ds_write_b128 v154, v[56:59]
	s_waitcnt lgkmcnt(0)
	ds_read_b128 v[56:59], v187
	s_waitcnt lgkmcnt(0)
	global_store_dwordx4 v[70:71], v[56:59], off
	v_pk_mul_f32 v[54:55], v[54:55], v[208:209] op_sel_hi:[1,0]
	s_nop 0
	v_pk_mul_f32 v[56:57], v[50:51], v[208:209] op_sel_hi:[1,0]
	v_pk_mul_f32 v[50:51], v[48:49], v[208:209] op_sel_hi:[1,0]
	v_cvt_pk_bf16_f32 v48, v52, v53
	v_cvt_pk_bf16_f32 v49, v54, v55
	s_nop 0
	v_cvt_pk_bf16_f32 v50, v50, v51
	v_cvt_pk_bf16_f32 v51, v56, v57
	ds_write_b128 v154, v[48:51]
	s_waitcnt lgkmcnt(0)
	ds_read_b128 v[48:51], v187
	s_waitcnt lgkmcnt(0)
	global_store_dwordx4 v[70:71], v[48:51], off offset:256
	s_nop 1
	v_add_u32_e32 v48, 0x90, v150
	s_nop 0
.LBB0_483:
	v_and_b32_e32 v48, 0x7df, v48
	v_mul_u32_u24_e32 v48, s39, v48
	v_lshlrev_b32_e32 v128, 1, v48
	v_lshl_add_u64 v[48:49], v[64:65], 0, v[128:129]
	v_lshl_add_u64 v[48:49], v[148:149], 1, v[48:49]
	s_nop 0
	v_pk_mul_f32 v[46:47], v[46:47], v[210:211] op_sel_hi:[1,0]
	v_pk_mul_f32 v[44:45], v[44:45], v[210:211] op_sel_hi:[1,0]
	v_pk_mul_f32 v[50:51], v[42:43], v[210:211] op_sel_hi:[1,0]
	v_pk_mul_f32 v[42:43], v[40:41], v[210:211] op_sel_hi:[1,0]
	v_cvt_pk_bf16_f32 v40, v44, v45
	v_cvt_pk_bf16_f32 v41, v46, v47
	v_pk_mul_f32 v[38:39], v[38:39], v[210:211] op_sel_hi:[1,0]
	v_cvt_pk_bf16_f32 v42, v42, v43
	v_cvt_pk_bf16_f32 v43, v50, v51
	ds_write_b128 v154, v[40:43]
	s_waitcnt lgkmcnt(0)
	ds_read_b128 v[40:43], v187
	s_waitcnt lgkmcnt(0)
	global_store_dwordx4 v[48:49], v[40:43], off
	v_pk_mul_f32 v[36:37], v[36:37], v[210:211] op_sel_hi:[1,0]
	s_nop 0
	v_pk_mul_f32 v[40:41], v[34:35], v[210:211] op_sel_hi:[1,0]
	v_pk_mul_f32 v[34:35], v[32:33], v[210:211] op_sel_hi:[1,0]
	v_cvt_pk_bf16_f32 v32, v36, v37
	v_cvt_pk_bf16_f32 v33, v38, v39
	v_add_u32_e32 v36, 0xa0, v150
	v_cvt_pk_bf16_f32 v34, v34, v35
	v_cvt_pk_bf16_f32 v35, v40, v41
	ds_write_b128 v154, v[32:35]
	s_waitcnt lgkmcnt(0)
	ds_read_b128 v[32:35], v187
	s_waitcnt lgkmcnt(0)
	global_store_dwordx4 v[48:49], v[32:35], off offset:256
	s_nop 1
	s_nop 0
	s_nop 0
	s_nop 0
.LBB0_485:
	v_and_b32_e32 v33, 0x7ef, v36
	v_mul_u32_u24_e32 v33, s39, v33
	v_lshlrev_b32_e32 v128, 1, v33
	v_lshl_add_u64 v[36:37], v[64:65], 0, v[128:129]
	v_lshl_add_u64 v[36:37], v[148:149], 1, v[36:37]
	s_nop 0
	v_pk_mul_f32 v[30:31], v[30:31], v[212:213] op_sel_hi:[1,0]
	v_pk_mul_f32 v[28:29], v[28:29], v[212:213] op_sel_hi:[1,0]
	v_pk_mul_f32 v[38:39], v[26:27], v[212:213] op_sel_hi:[1,0]
	v_pk_mul_f32 v[26:27], v[24:25], v[212:213] op_sel_hi:[1,0]
	v_cvt_pk_bf16_f32 v24, v28, v29
	v_cvt_pk_bf16_f32 v25, v30, v31
	v_pk_mul_f32 v[20:21], v[20:21], v[212:213] op_sel_hi:[1,0]
	v_cvt_pk_bf16_f32 v26, v26, v27
	v_cvt_pk_bf16_f32 v27, v38, v39
	ds_write_b128 v154, v[24:27]
	s_waitcnt lgkmcnt(0)
	ds_read_b128 v[24:27], v187
	s_waitcnt lgkmcnt(0)
	global_store_dwordx4 v[36:37], v[24:27], off
	v_pk_mul_f32 v[22:23], v[22:23], v[212:213] op_sel_hi:[1,0]
	s_nop 0
	v_pk_mul_f32 v[24:25], v[18:19], v[212:213] op_sel_hi:[1,0]
	v_pk_mul_f32 v[18:19], v[16:17], v[212:213] op_sel_hi:[1,0]
	v_cvt_pk_bf16_f32 v16, v20, v21
	v_cvt_pk_bf16_f32 v17, v22, v23
	s_nop 0
	v_cvt_pk_bf16_f32 v18, v18, v19
	v_cvt_pk_bf16_f32 v19, v24, v25
	ds_write_b128 v154, v[16:19]
	s_waitcnt lgkmcnt(0)
	ds_read_b128 v[16:19], v187
	s_waitcnt lgkmcnt(0)
	global_store_dwordx4 v[36:37], v[16:19], off offset:256
	s_nop 1
	v_add_u32_e32 v16, 0xb0, v150
	s_nop 0
.LBB0_487:
	v_and_b32_e32 v16, 0x7ff, v16
	v_mul_u32_u24_e32 v16, s39, v16
	v_lshlrev_b32_e32 v128, 1, v16
	v_lshl_add_u64 v[16:17], v[64:65], 0, v[128:129]
	v_lshl_add_u64 v[16:17], v[148:149], 1, v[16:17]
	s_nop 0
	v_pk_mul_f32 v[14:15], v[14:15], v[214:215] op_sel_hi:[1,0]
	v_pk_mul_f32 v[12:13], v[12:13], v[214:215] op_sel_hi:[1,0]
	v_pk_mul_f32 v[18:19], v[10:11], v[214:215] op_sel_hi:[1,0]
	v_pk_mul_f32 v[10:11], v[8:9], v[214:215] op_sel_hi:[1,0]
	v_cvt_pk_bf16_f32 v8, v12, v13
	v_cvt_pk_bf16_f32 v9, v14, v15
	s_and_b64 vcc, exec, s[6:7]
	v_cvt_pk_bf16_f32 v10, v10, v11
	v_cvt_pk_bf16_f32 v11, v18, v19
	ds_write_b128 v154, v[8:11]
	s_waitcnt lgkmcnt(0)
	ds_read_b128 v[8:11], v187
	s_waitcnt lgkmcnt(0)
	global_store_dwordx4 v[16:17], v[8:11], off
	s_mov_b64 s[6:7], -1
	v_pk_mul_f32 v[6:7], v[6:7], v[214:215] op_sel_hi:[1,0]
	v_pk_mul_f32 v[8:9], v[2:3], v[214:215] op_sel_hi:[1,0]
	v_pk_mul_f32 v[2:3], v[0:1], v[214:215] op_sel_hi:[1,0]
	v_pk_mul_f32 v[4:5], v[4:5], v[214:215] op_sel_hi:[1,0]
	s_nop 0
	v_cvt_pk_bf16_f32 v0, v4, v5
	v_cvt_pk_bf16_f32 v1, v6, v7
	v_cvt_pk_bf16_f32 v2, v2, v3
	v_cvt_pk_bf16_f32 v3, v8, v9
	ds_write_b128 v154, v[0:3]
	s_waitcnt lgkmcnt(0)
	ds_read_b128 v[0:3], v187
	s_waitcnt lgkmcnt(0)
	global_store_dwordx4 v[16:17], v[0:3], off offset:256
	s_cbranch_vccnz .LBB0_458
	s_andn2_b64 vcc, exec, s[18:19]
	s_cbranch_vccnz .LBB0_457
	s_barrier
	s_branch .LBB0_457
